# stack18: stack15 + FFN weight conversions (W_up with folded gain, W_down) moved from the conversion phase into the merge-phase tail, done by the CUs that have no sample-row job
# speedup vs baseline: 1.0151x; 1.0151x over previous
.LBB0_108:
	s_or_b64 exec, exec, s[4:5]
	s_add_u32 s4, s96, 0x1e029800
	s_addc_u32 s5, s97, 0
	v_writelane_b32 v249, s4, 0
	s_nop 1
	v_writelane_b32 v249, s5, 1
	s_mov_b32 s4, 0xb0000
	v_cmp_gt_i32_e32 vcc, s4, v16
	s_and_saveexec_b64 s[4:5], vcc
	s_cbranch_execz .LBB0_131
	s_branch .LBB0_131
	s_load_dwordx4 s[12:15], s[26:27], 0x108
	v_readlane_b32 s6, v250, 58
	s_mul_i32 s8, s6, 0x1600000
	v_readlane_b32 s7, v250, 59
	s_mov_b64 s[6:7], 0
	s_waitcnt lgkmcnt(0)
	s_add_u32 s8, s14, s8
	s_addc_u32 s9, s15, 0
	s_lshl_b64 s[2:3], s[2:3], 2
	s_add_u32 s2, s12, s2
	s_addc_u32 s3, s13, s3
	s_cmp_lg_u64 s[12:13], 0
	s_cselect_b64 s[10:11], -1, 0
	v_mov_b32_e32 v17, v16
	s_branch .LBB0_112

.LBB0_131:
	s_or_b64 exec, exec, s[4:5]
	s_add_u32 s12, s96, 0x1eb29800
	s_mov_b32 s2, 0x58000
	s_addc_u32 s13, s97, 0
	v_cmp_gt_i32_e32 vcc, s2, v16
	s_and_saveexec_b64 s[2:3], vcc
	s_cbranch_execz .LBB0_150
	s_branch .LBB0_150
	s_load_dwordx2 s[6:7], s[26:27], 0x128
	v_readlane_b32 s4, v250, 58
	s_mul_i32 s8, s4, 0xb00000
	v_readlane_b32 s5, v250, 59
	s_movk_i32 s4, 0xb00
	s_waitcnt lgkmcnt(0)
	s_add_u32 s6, s6, s8
	v_mul_lo_u32 v0, v16, s4
	s_mov_b64 s[4:5], 0
	s_addc_u32 s7, s7, 0
	v_mov_b32_e32 v1, v16
	s_branch .LBB0_134

.LBB0_1186:
	s_cmp_gt_u32 s90, 32
	s_cselect_b32 s36, 32, 0
	s_cmp_lt_u32 s21, s36
	s_cbranch_scc1 .Lwt_done
	v_readlane_b32 s37, v250, 58
	v_readlane_b32 s38, v250, 52
	v_readlane_b32 s39, v250, 53
	v_readfirstlane_b32 s40, v224
	v_and_b32_e32 v0, 63, v224
	s_lshr_b32 s40, s40, 6
	s_sub_u32 s41, s21, s36
	s_lshl_b32 s41, s41, 3
	s_add_u32 s40, s40, s41
	s_sub_u32 s41, s90, s36
	s_lshl_b32 s41, s41, 3
	s_load_dwordx4 s[44:47], s[38:39], 0x108
	v_lshlrev_b32_e32 v1, 2, v0
	v_add_u32_e32 v2, 0x5800, v1
	v_add_u32_e32 v3, 0xb000, v1
	v_add_u32_e32 v4, 0x10800, v1
	v_add_u32_e32 v5, 0x16000, v1
	v_add_u32_e32 v6, 0x1b800, v1
	v_add_u32_e32 v7, 0x21000, v1
	v_add_u32_e32 v8, 0x26800, v1
	v_lshlrev_b32_e32 v9, 11, v0
	s_add_u32 s48, s96, 0x1e029800
	s_addc_u32 s49, s97, 0
	s_mul_i32 s42, s37, 0x1600000
	s_lshl_b32 s43, s37, 12
	s_waitcnt lgkmcnt(0)
	s_add_u32 s46, s46, s42
	s_addc_u32 s47, s47, 0
	s_add_u32 s44, s44, s43
	s_addc_u32 s45, s45, 0
	s_mov_b32 s50, s40
.Lwt_up_loop:
	s_cmp_ge_u32 s50, 0x2c00
	s_cbranch_scc1 .Lwt_up_end
	s_mul_hi_u32 s51, s50, 0x2e8ba2f
	s_mul_i32 s52, s51, 0x58
	s_sub_u32 s52, s50, s52
	s_lshr_b32 s53, s52, 2
	s_lshl_b32 s53, s53, 7
	s_and_b32 s54, s52, 3
	s_lshl_b32 s54, s54, 6
	s_add_u32 s53, s53, s54
	s_cmp_ge_u32 s54, 0x80
	s_cselect_b32 s54, 0xa80, 0
	s_add_u32 s53, s53, s54
	s_mul_i32 s54, s51, 0x2c000
	s_lshl_b32 s53, s53, 2
	s_add_u32 s54, s54, s53
	s_add_u32 s56, s46, s54
	s_addc_u32 s57, s47, 0
	global_load_dword v16, v1, s[56:57]
	global_load_dword v17, v2, s[56:57]
	global_load_dword v18, v3, s[56:57]
	global_load_dword v19, v4, s[56:57]
	global_load_dword v20, v5, s[56:57]
	global_load_dword v21, v6, s[56:57]
	global_load_dword v22, v7, s[56:57]
	global_load_dword v23, v8, s[56:57]
	s_lshl_b32 s55, s51, 5
	s_load_dwordx8 s[64:71], s[44:45], s55
	s_lshl_b32 s58, s52, 17
	s_lshl_b32 s59, s51, 4
	s_add_u32 s58, s58, s59
	s_add_u32 s58, s48, s58
	s_addc_u32 s59, s49, 0
	s_waitcnt vmcnt(0) lgkmcnt(0)
	v_mul_f32_e32 v16, s64, v16
	v_mul_f32_e32 v17, s65, v17
	v_mul_f32_e32 v18, s66, v18
	v_mul_f32_e32 v19, s67, v19
	v_mul_f32_e32 v20, s68, v20
	v_mul_f32_e32 v21, s69, v21
	v_mul_f32_e32 v22, s70, v22
	v_mul_f32_e32 v23, s71, v23
	v_cvt_pk_bf16_f32 v16, v16, v17
	v_cvt_pk_bf16_f32 v17, v18, v19
	v_cvt_pk_bf16_f32 v18, v20, v21
	v_cvt_pk_bf16_f32 v19, v22, v23
	global_store_dwordx4 v9, v[16:19], s[58:59]
	s_add_u32 s50, s50, s41
	s_branch .Lwt_up_loop
.Lwt_up_end:
	s_load_dwordx2 s[46:47], s[38:39], 0x128
	v_add_u32_e32 v2, 0x1000, v1
	v_add_u32_e32 v3, 0x2000, v1
	v_add_u32_e32 v4, 0x3000, v1
	v_add_u32_e32 v5, 0x4000, v1
	v_add_u32_e32 v6, 0x5000, v1
	v_add_u32_e32 v7, 0x6000, v1
	v_add_u32_e32 v8, 0x7000, v1
	v_mul_u32_u24_e32 v9, 0x1600, v0
	s_add_u32 s48, s96, 0x1eb29800
	s_addc_u32 s49, s97, 0
	s_mul_i32 s42, s37, 0xb00000
	s_waitcnt lgkmcnt(0)
	s_add_u32 s46, s46, s42
	s_addc_u32 s47, s47, 0
	s_mov_b32 s50, s40
.Lwt_dn_loop:
	s_cmp_ge_u32 s50, 0x1600
	s_cbranch_scc1 .Lwt_done
	s_lshr_b32 s51, s50, 4
	s_and_b32 s52, s50, 15
	s_lshl_b32 s54, s51, 15
	s_lshl_b32 s53, s52, 8
	s_add_u32 s54, s54, s53
	s_add_u32 s56, s46, s54
	s_addc_u32 s57, s47, 0
	global_load_dword v16, v1, s[56:57]
	global_load_dword v17, v2, s[56:57]
	global_load_dword v18, v3, s[56:57]
	global_load_dword v19, v4, s[56:57]
	global_load_dword v20, v5, s[56:57]
	global_load_dword v21, v6, s[56:57]
	global_load_dword v22, v7, s[56:57]
	global_load_dword v23, v8, s[56:57]
	s_mul_i32 s58, s52, 0x58000
	s_lshl_b32 s59, s51, 4
	s_add_u32 s58, s58, s59
	s_add_u32 s58, s48, s58
	s_addc_u32 s59, s49, 0
	s_waitcnt vmcnt(0)
	v_cvt_pk_bf16_f32 v16, v16, v17
	v_cvt_pk_bf16_f32 v17, v18, v19
	v_cvt_pk_bf16_f32 v18, v20, v21
	v_cvt_pk_bf16_f32 v19, v22, v23
	global_store_dwordx4 v9, v[16:19], s[58:59]
	s_add_u32 s50, s50, s41
	s_branch .Lwt_dn_loop
